# v5: plus GU SwiGLU epilogue reads all 8 per-row rstd values from LDS up front (one wait instead of eight)
# speedup vs baseline: 1.0105x; 1.0032x over previous
; __device__ __forceinline__ unsigned cvt_pk_bf16(float lo, float hi) { unsigned r; asm volatile("v_cvt_pk_bf16_f32 %0, %1, %2" : "=v"(r) : "v"(lo), "v"(hi)); return r; }
; __device__ __forceinline__ lds_f32* stats_tab() { return (lds_f32*)(size_t)(147456 - 4096); }
; __device__ __forceinline__ float silu_mul(float g, float u) { return g * __builtin_amdgcn_rcpf(1.0f + __expf(-g)) * u; }
;     __device__ __forceinline__ void operator()(const f32x4 (&acc)[2][2][4][2], const Unit& u, int wr, int wc, int fr, int fq) const {
;     ...
;         stats_table(rs, u.pm * BM, (wr * 4 + wc) * 64 + fq * 16 + fr); const lds_f32* tab = stats_tab();
; #pragma unroll
;         for (int ai = 0; ai < 2; ++ai)
; #pragma unroll
;             for (int m = 0; m < 4; ++m) { const int row = row0 + ai * HALF + m * 16; bf16_t* rowp = O + (size_t)row * ldc + col0; const float rsc = tab[wr * 64 + fr + ai * HALF + m * 16];
;                 const f32x4 g0 = acc[ai][0][m][0] * rsc, g1 = acc[ai][0][m][1] * rsc, u0 = acc[ai][1][m][0] * rsc, u1 = acc[ai][1][m][1] * rsc;
;                 u32x4 w;
;                 w.x = cvt_pk_bf16(silu_mul(g0[0], u0[0]), silu_mul(g0[1], u0[1])); w.y = cvt_pk_bf16(silu_mul(g0[2], u0[2]), silu_mul(g0[3], u0[3]));
;                 w.z = cvt_pk_bf16(silu_mul(g1[0], u1[0]), silu_mul(g1[1], u1[1])); w.w = cvt_pk_bf16(silu_mul(g1[2], u1[2]), silu_mul(g1[3], u1[3]));
;                 *(u32x4*)(rowp) = w; }
.LBB0_643:
	s_lshl_b32 s3, s3, 7
	v_lshrrev_b32_e32 v0, 1, v143
	s_or_b32 s3, s3, s79
	v_and_b32_e32 v0, 56, v0
	v_add_u32_e32 v144, s3, v0
	v_lshl_add_u32 v0, v142, 2, s90
	ds_read_b32 v152, v0
	ds_read_b32 v174, v0 offset:64
	ds_read_b32 v176, v0 offset:128
	ds_read_b32 v178, v0 offset:192
	ds_read_b32 v180, v0 offset:512
	ds_read_b32 v182, v0 offset:576
	ds_read_b32 v184, v0 offset:640
	ds_read_b32 v186, v0 offset:704
	s_add_i32 s19, s19, s77
	v_or_b32_e32 v151, s19, v142
	v_ashrrev_i32_e32 v145, 31, v144
	v_mov_b64_e32 v[142:143], s[12:13]
	s_waitcnt lgkmcnt(0)
	v_pk_mul_f32 v[126:127], v[126:127], v[152:153] op_sel_hi:[1,0]
	v_pk_mul_f32 v[154:155], v[116:117], v[152:153] op_sel_hi:[1,0]
	v_pk_mul_f32 v[116:117], v[114:115], v[152:153] op_sel_hi:[1,0]
	v_mul_f32_e32 v114, 0xbfb8aa3b, v126
	v_mul_f32_e32 v115, 0xbfb8aa3b, v127
	v_exp_f32_e32 v114, v114
	v_exp_f32_e32 v115, v115
	v_pk_mul_f32 v[118:119], v[118:119], v[152:153] op_sel_hi:[1,0]
	v_pk_mul_f32 v[128:129], v[128:129], v[152:153] op_sel_hi:[1,0]
	v_add_f32_e32 v114, 1.0, v114
	v_add_f32_e32 v115, 1.0, v115
	v_rcp_f32_e32 v114, v114
	v_rcp_f32_e32 v115, v115
	v_pk_mul_f32 v[120:121], v[120:121], v[152:153] op_sel_hi:[1,0]
	v_pk_mul_f32 v[122:123], v[122:123], v[152:153] op_sel_hi:[1,0]
	v_mul_f32_e32 v114, v126, v114
	v_mul_f32_e32 v115, v127, v115
	v_mul_f32_e32 v114, v118, v114
	v_mul_f32_e32 v115, v119, v115
	v_cvt_pk_bf16_f32 v114, v114, v115
	v_mul_f32_e32 v115, 0xbfb8aa3b, v128
	v_mul_f32_e32 v118, 0xbfb8aa3b, v129
	v_exp_f32_e32 v115, v115
	v_exp_f32_e32 v118, v118
	v_pk_mul_f32 v[124:125], v[124:125], v[152:153] op_sel_hi:[1,0]
	v_mad_i64_i32 v[146:147], s[28:29], v151, s82, v[142:143]
	v_add_f32_e32 v115, 1.0, v115
	v_add_f32_e32 v118, 1.0, v118
	v_rcp_f32_e32 v115, v115
	v_rcp_f32_e32 v118, v118
	v_lshlrev_b64 v[144:145], 1, v[144:145]
	v_lshl_add_u64 v[146:147], v[146:147], 0, v[144:145]
	v_mul_f32_e32 v115, v128, v115
	v_mul_f32_e32 v118, v129, v118
	v_mul_f32_e32 v115, v120, v115
	v_mul_f32_e32 v118, v121, v118
	v_cvt_pk_bf16_f32 v115, v115, v118
	v_mul_f32_e32 v118, 0xbfb8aa3b, v122
	v_exp_f32_e32 v118, v118
	s_andn2_b64 vcc, exec, s[6:7]
	v_add_f32_e32 v118, 1.0, v118
	v_rcp_f32_e32 v118, v118
	s_nop 0
	v_mul_f32_e32 v118, v122, v118
	v_mul_f32_e32 v116, v116, v118
	v_mul_f32_e32 v118, 0xbfb8aa3b, v123
	v_exp_f32_e32 v118, v118
	s_nop 0
	v_add_f32_e32 v118, 1.0, v118
	v_rcp_f32_e32 v118, v118
	s_nop 0
	v_mul_f32_e32 v118, v123, v118
	v_mul_f32_e32 v117, v117, v118
	v_cvt_pk_bf16_f32 v116, v116, v117
	v_mul_f32_e32 v117, 0xbfb8aa3b, v124
	v_exp_f32_e32 v117, v117
	v_mul_f32_e32 v118, 0xbfb8aa3b, v125
	v_exp_f32_e32 v118, v118
	v_add_f32_e32 v117, 1.0, v117
	v_rcp_f32_e32 v117, v117
	v_add_f32_e32 v118, 1.0, v118
	v_rcp_f32_e32 v118, v118
	v_mul_f32_e32 v117, v124, v117
	v_mul_f32_e32 v117, v154, v117
	v_mul_f32_e32 v118, v125, v118
	v_mul_f32_e32 v118, v155, v118
	v_cvt_pk_bf16_f32 v117, v117, v118
	global_store_dwordx4 v[146:147], v[114:117], off
	v_pk_mul_f32 v[110:111], v[110:111], v[174:175] op_sel_hi:[1,0]
	v_pk_mul_f32 v[118:119], v[100:101], v[174:175] op_sel_hi:[1,0]
	v_pk_mul_f32 v[100:101], v[98:99], v[174:175] op_sel_hi:[1,0]
	v_mul_f32_e32 v98, 0xbfb8aa3b, v110
	v_mul_f32_e32 v99, 0xbfb8aa3b, v111
	v_exp_f32_e32 v98, v98
	v_exp_f32_e32 v99, v99
	v_pk_mul_f32 v[102:103], v[102:103], v[174:175] op_sel_hi:[1,0]
	v_pk_mul_f32 v[112:113], v[112:113], v[174:175] op_sel_hi:[1,0]
	v_add_f32_e32 v98, 1.0, v98
	v_add_f32_e32 v99, 1.0, v99
	v_rcp_f32_e32 v98, v98
	v_rcp_f32_e32 v99, v99
	v_pk_mul_f32 v[104:105], v[104:105], v[174:175] op_sel_hi:[1,0]
	v_pk_mul_f32 v[106:107], v[106:107], v[174:175] op_sel_hi:[1,0]
	v_mul_f32_e32 v98, v110, v98
	v_mul_f32_e32 v99, v111, v99
	v_mul_f32_e32 v98, v102, v98
	v_mul_f32_e32 v99, v103, v99
	v_cvt_pk_bf16_f32 v98, v98, v99
	v_mul_f32_e32 v99, 0xbfb8aa3b, v112
	v_mul_f32_e32 v102, 0xbfb8aa3b, v113
	v_exp_f32_e32 v99, v99
	v_exp_f32_e32 v102, v102
	v_pk_mul_f32 v[108:109], v[108:109], v[174:175] op_sel_hi:[1,0]
	v_or_b32_e32 v114, 16, v151
	v_add_f32_e32 v99, 1.0, v99
	v_add_f32_e32 v102, 1.0, v102
	v_rcp_f32_e32 v99, v99
	v_rcp_f32_e32 v102, v102
	v_mad_i64_i32 v[114:115], s[28:29], v114, s82, v[142:143]
	v_mul_f32_e32 v99, v112, v99
	v_mul_f32_e32 v102, v113, v102
	v_mul_f32_e32 v99, v104, v99
	v_mul_f32_e32 v102, v105, v102
	v_cvt_pk_bf16_f32 v99, v99, v102
	v_mul_f32_e32 v102, 0xbfb8aa3b, v106
	v_exp_f32_e32 v102, v102
	v_lshl_add_u64 v[114:115], v[114:115], 0, v[144:145]
	v_add_f32_e32 v102, 1.0, v102
	v_rcp_f32_e32 v102, v102
	s_nop 0
	v_mul_f32_e32 v102, v106, v102
	v_mul_f32_e32 v100, v100, v102
	v_mul_f32_e32 v102, 0xbfb8aa3b, v107
	v_exp_f32_e32 v102, v102
	s_nop 0
	v_add_f32_e32 v102, 1.0, v102
	v_rcp_f32_e32 v102, v102
	s_nop 0
	v_mul_f32_e32 v102, v107, v102
	v_mul_f32_e32 v101, v101, v102
	v_cvt_pk_bf16_f32 v100, v100, v101
	v_mul_f32_e32 v101, 0xbfb8aa3b, v108
	v_exp_f32_e32 v101, v101
	v_mul_f32_e32 v102, 0xbfb8aa3b, v109
	v_exp_f32_e32 v102, v102
	v_add_f32_e32 v101, 1.0, v101
	v_rcp_f32_e32 v101, v101
	v_add_f32_e32 v102, 1.0, v102
	v_rcp_f32_e32 v102, v102
	v_mul_f32_e32 v101, v108, v101
	v_mul_f32_e32 v101, v118, v101
	v_mul_f32_e32 v102, v109, v102
	v_mul_f32_e32 v102, v119, v102
	v_cvt_pk_bf16_f32 v101, v101, v102
	global_store_dwordx4 v[114:115], v[98:101], off
	v_pk_mul_f32 v[94:95], v[94:95], v[176:177] op_sel_hi:[1,0]
	v_pk_mul_f32 v[102:103], v[84:85], v[176:177] op_sel_hi:[1,0]
	v_pk_mul_f32 v[84:85], v[82:83], v[176:177] op_sel_hi:[1,0]
	v_mul_f32_e32 v82, 0xbfb8aa3b, v94
	v_mul_f32_e32 v83, 0xbfb8aa3b, v95
	v_exp_f32_e32 v82, v82
	v_exp_f32_e32 v83, v83
	v_pk_mul_f32 v[86:87], v[86:87], v[176:177] op_sel_hi:[1,0]
; __device__ __forceinline__ unsigned cvt_pk_bf16(float lo, float hi) { unsigned r; asm volatile("v_cvt_pk_bf16_f32 %0, %1, %2" : "=v"(r) : "v"(lo), "v"(hi)); return r; }
; __device__ __forceinline__ float silu_mul(float g, float u) { return g * __builtin_amdgcn_rcpf(1.0f + __expf(-g)) * u; }
;     __device__ __forceinline__ void operator()(const f32x4 (&acc)[2][2][4][2], const Unit& u, int wr, int wc, int fr, int fq) const {
;     ...
;             for (int m = 0; m < 4; ++m) { const int row = row0 + ai * HALF + m * 16; bf16_t* rowp = O + (size_t)row * ldc + col0; const float rsc = tab[wr * 64 + fr + ai * HALF + m * 16];
;                 const f32x4 g0 = acc[ai][0][m][0] * rsc, g1 = acc[ai][0][m][1] * rsc, u0 = acc[ai][1][m][0] * rsc, u1 = acc[ai][1][m][1] * rsc;
;                 u32x4 w;
;                 w.x = cvt_pk_bf16(silu_mul(g0[0], u0[0]), silu_mul(g0[1], u0[1])); w.y = cvt_pk_bf16(silu_mul(g0[2], u0[2]), silu_mul(g0[3], u0[3]));
;                 w.z = cvt_pk_bf16(silu_mul(g1[0], u1[0]), silu_mul(g1[1], u1[1])); w.w = cvt_pk_bf16(silu_mul(g1[2], u1[2]), silu_mul(g1[3], u1[3]));
;                 *(u32x4*)(rowp) = w; }
	v_pk_mul_f32 v[96:97], v[96:97], v[176:177] op_sel_hi:[1,0]
	v_add_f32_e32 v82, 1.0, v82
	v_add_f32_e32 v83, 1.0, v83
	v_rcp_f32_e32 v82, v82
	v_rcp_f32_e32 v83, v83
	v_pk_mul_f32 v[88:89], v[88:89], v[176:177] op_sel_hi:[1,0]
	v_pk_mul_f32 v[90:91], v[90:91], v[176:177] op_sel_hi:[1,0]
	v_mul_f32_e32 v82, v94, v82
	v_mul_f32_e32 v83, v95, v83
	v_mul_f32_e32 v82, v86, v82
	v_mul_f32_e32 v83, v87, v83
	v_cvt_pk_bf16_f32 v82, v82, v83
	v_mul_f32_e32 v83, 0xbfb8aa3b, v96
	v_mul_f32_e32 v86, 0xbfb8aa3b, v97
	v_exp_f32_e32 v83, v83
	v_exp_f32_e32 v86, v86
	v_pk_mul_f32 v[92:93], v[92:93], v[176:177] op_sel_hi:[1,0]
	v_or_b32_e32 v98, 32, v151
	v_add_f32_e32 v83, 1.0, v83
	v_add_f32_e32 v86, 1.0, v86
	v_rcp_f32_e32 v83, v83
	v_rcp_f32_e32 v86, v86
	v_mad_i64_i32 v[98:99], s[28:29], v98, s82, v[142:143]
	v_mul_f32_e32 v83, v96, v83
	v_mul_f32_e32 v86, v97, v86
	v_mul_f32_e32 v83, v88, v83
	v_mul_f32_e32 v86, v89, v86
	v_cvt_pk_bf16_f32 v83, v83, v86
	v_mul_f32_e32 v86, 0xbfb8aa3b, v90
	v_exp_f32_e32 v86, v86
	v_lshl_add_u64 v[98:99], v[98:99], 0, v[144:145]
	v_add_f32_e32 v86, 1.0, v86
	v_rcp_f32_e32 v86, v86
	s_nop 0
	v_mul_f32_e32 v86, v90, v86
	v_mul_f32_e32 v84, v84, v86
	v_mul_f32_e32 v86, 0xbfb8aa3b, v91
	v_exp_f32_e32 v86, v86
	s_nop 0
	v_add_f32_e32 v86, 1.0, v86
	v_rcp_f32_e32 v86, v86
	s_nop 0
	v_mul_f32_e32 v86, v91, v86
	v_mul_f32_e32 v85, v85, v86
	v_cvt_pk_bf16_f32 v84, v84, v85
	v_mul_f32_e32 v85, 0xbfb8aa3b, v92
	v_exp_f32_e32 v85, v85
	v_mul_f32_e32 v86, 0xbfb8aa3b, v93
	v_exp_f32_e32 v86, v86
	v_add_f32_e32 v85, 1.0, v85
	v_rcp_f32_e32 v85, v85
	v_add_f32_e32 v86, 1.0, v86
	v_rcp_f32_e32 v86, v86
	v_mul_f32_e32 v85, v92, v85
	v_mul_f32_e32 v85, v102, v85
	v_mul_f32_e32 v86, v93, v86
	v_mul_f32_e32 v86, v103, v86
	v_cvt_pk_bf16_f32 v85, v85, v86
	global_store_dwordx4 v[98:99], v[82:85], off
	v_pk_mul_f32 v[78:79], v[78:79], v[178:179] op_sel_hi:[1,0]
	v_pk_mul_f32 v[86:87], v[68:69], v[178:179] op_sel_hi:[1,0]
	v_pk_mul_f32 v[68:69], v[66:67], v[178:179] op_sel_hi:[1,0]
	v_mul_f32_e32 v66, 0xbfb8aa3b, v78
	v_mul_f32_e32 v67, 0xbfb8aa3b, v79
	v_exp_f32_e32 v66, v66
	v_exp_f32_e32 v67, v67
	v_pk_mul_f32 v[70:71], v[70:71], v[178:179] op_sel_hi:[1,0]
	v_pk_mul_f32 v[80:81], v[80:81], v[178:179] op_sel_hi:[1,0]
	v_add_f32_e32 v66, 1.0, v66
	v_add_f32_e32 v67, 1.0, v67
	v_rcp_f32_e32 v66, v66
	v_rcp_f32_e32 v67, v67
	v_pk_mul_f32 v[72:73], v[72:73], v[178:179] op_sel_hi:[1,0]
	v_pk_mul_f32 v[74:75], v[74:75], v[178:179] op_sel_hi:[1,0]
	v_mul_f32_e32 v66, v78, v66
	v_mul_f32_e32 v67, v79, v67
	v_mul_f32_e32 v66, v70, v66
	v_mul_f32_e32 v67, v71, v67
	v_cvt_pk_bf16_f32 v66, v66, v67
	v_mul_f32_e32 v67, 0xbfb8aa3b, v80
	v_mul_f32_e32 v70, 0xbfb8aa3b, v81
	v_exp_f32_e32 v67, v67
	v_exp_f32_e32 v70, v70
	v_pk_mul_f32 v[76:77], v[76:77], v[178:179] op_sel_hi:[1,0]
	v_or_b32_e32 v82, 48, v151
	v_add_f32_e32 v67, 1.0, v67
	v_add_f32_e32 v70, 1.0, v70
	v_rcp_f32_e32 v67, v67
	v_rcp_f32_e32 v70, v70
	v_mad_i64_i32 v[82:83], s[28:29], v82, s82, v[142:143]
	v_mul_f32_e32 v67, v80, v67
	v_mul_f32_e32 v70, v81, v70
	v_mul_f32_e32 v67, v72, v67
	v_mul_f32_e32 v70, v73, v70
	v_cvt_pk_bf16_f32 v67, v67, v70
	v_mul_f32_e32 v70, 0xbfb8aa3b, v74
	v_exp_f32_e32 v70, v70
	v_lshl_add_u64 v[82:83], v[82:83], 0, v[144:145]
	v_add_f32_e32 v70, 1.0, v70
	v_rcp_f32_e32 v70, v70
	s_nop 0
	v_mul_f32_e32 v70, v74, v70
	v_mul_f32_e32 v68, v68, v70
	v_mul_f32_e32 v70, 0xbfb8aa3b, v75
	v_exp_f32_e32 v70, v70
	s_nop 0
	v_add_f32_e32 v70, 1.0, v70
	v_rcp_f32_e32 v70, v70
	s_nop 0
	v_mul_f32_e32 v70, v75, v70
	v_mul_f32_e32 v69, v69, v70
	v_cvt_pk_bf16_f32 v68, v68, v69
	v_mul_f32_e32 v69, 0xbfb8aa3b, v76
	v_exp_f32_e32 v69, v69
	v_mul_f32_e32 v70, 0xbfb8aa3b, v77
	v_exp_f32_e32 v70, v70
	v_add_f32_e32 v69, 1.0, v69
	v_rcp_f32_e32 v69, v69
	v_add_f32_e32 v70, 1.0, v70
	v_rcp_f32_e32 v70, v70
	v_mul_f32_e32 v69, v76, v69
	v_mul_f32_e32 v69, v86, v69
	v_mul_f32_e32 v70, v77, v70
	v_mul_f32_e32 v70, v87, v70
	v_cvt_pk_bf16_f32 v69, v69, v70
	global_store_dwordx4 v[82:83], v[66:69], off
	v_pk_mul_f32 v[62:63], v[62:63], v[180:181] op_sel_hi:[1,0]
	v_pk_mul_f32 v[70:71], v[52:53], v[180:181] op_sel_hi:[1,0]
	v_pk_mul_f32 v[52:53], v[50:51], v[180:181] op_sel_hi:[1,0]
	v_mul_f32_e32 v50, 0xbfb8aa3b, v62
	v_mul_f32_e32 v51, 0xbfb8aa3b, v63
	v_exp_f32_e32 v50, v50
	v_exp_f32_e32 v51, v51
	v_pk_mul_f32 v[54:55], v[54:55], v[180:181] op_sel_hi:[1,0]
	v_pk_mul_f32 v[64:65], v[64:65], v[180:181] op_sel_hi:[1,0]
	v_add_f32_e32 v50, 1.0, v50
	v_add_f32_e32 v51, 1.0, v51
	v_rcp_f32_e32 v50, v50
	v_rcp_f32_e32 v51, v51
	v_pk_mul_f32 v[56:57], v[56:57], v[180:181] op_sel_hi:[1,0]
	v_pk_mul_f32 v[58:59], v[58:59], v[180:181] op_sel_hi:[1,0]
	v_mul_f32_e32 v50, v62, v50
	v_mul_f32_e32 v51, v63, v51
	v_mul_f32_e32 v50, v54, v50
	v_mul_f32_e32 v51, v55, v51
	v_cvt_pk_bf16_f32 v50, v50, v51
	v_mul_f32_e32 v51, 0xbfb8aa3b, v64
	v_mul_f32_e32 v54, 0xbfb8aa3b, v65
	v_exp_f32_e32 v51, v51
	v_exp_f32_e32 v54, v54
	v_pk_mul_f32 v[60:61], v[60:61], v[180:181] op_sel_hi:[1,0]
	v_add_u32_e32 v66, 0x80, v151
	v_add_f32_e32 v51, 1.0, v51
	v_add_f32_e32 v54, 1.0, v54
	v_rcp_f32_e32 v51, v51
	v_rcp_f32_e32 v54, v54
	v_mad_i64_i32 v[66:67], s[28:29], v66, s82, v[142:143]
	v_mul_f32_e32 v51, v64, v51
	v_mul_f32_e32 v54, v65, v54
	v_mul_f32_e32 v51, v56, v51
	v_mul_f32_e32 v54, v57, v54
	v_cvt_pk_bf16_f32 v51, v51, v54
	v_mul_f32_e32 v54, 0xbfb8aa3b, v58
	v_exp_f32_e32 v54, v54
	v_lshl_add_u64 v[66:67], v[66:67], 0, v[144:145]
	v_add_f32_e32 v54, 1.0, v54
	v_rcp_f32_e32 v54, v54
	s_nop 0
	v_mul_f32_e32 v54, v58, v54
	v_mul_f32_e32 v52, v52, v54
	v_mul_f32_e32 v54, 0xbfb8aa3b, v59
	v_exp_f32_e32 v54, v54
; __device__ __forceinline__ unsigned cvt_pk_bf16(float lo, float hi) { unsigned r; asm volatile("v_cvt_pk_bf16_f32 %0, %1, %2" : "=v"(r) : "v"(lo), "v"(hi)); return r; }
; __device__ __forceinline__ float silu_mul(float g, float u) { return g * __builtin_amdgcn_rcpf(1.0f + __expf(-g)) * u; }
;     __device__ __forceinline__ void operator()(const f32x4 (&acc)[2][2][4][2], const Unit& u, int wr, int wc, int fr, int fq) const {
;     ...
;             for (int m = 0; m < 4; ++m) { const int row = row0 + ai * HALF + m * 16; bf16_t* rowp = O + (size_t)row * ldc + col0; const float rsc = tab[wr * 64 + fr + ai * HALF + m * 16];
;                 const f32x4 g0 = acc[ai][0][m][0] * rsc, g1 = acc[ai][0][m][1] * rsc, u0 = acc[ai][1][m][0] * rsc, u1 = acc[ai][1][m][1] * rsc;
;                 u32x4 w;
;                 w.x = cvt_pk_bf16(silu_mul(g0[0], u0[0]), silu_mul(g0[1], u0[1])); w.y = cvt_pk_bf16(silu_mul(g0[2], u0[2]), silu_mul(g0[3], u0[3]));
;                 w.z = cvt_pk_bf16(silu_mul(g1[0], u1[0]), silu_mul(g1[1], u1[1])); w.w = cvt_pk_bf16(silu_mul(g1[2], u1[2]), silu_mul(g1[3], u1[3]));
;                 *(u32x4*)(rowp) = w; }
	s_nop 0
	v_add_f32_e32 v54, 1.0, v54
	v_rcp_f32_e32 v54, v54
	s_nop 0
	v_mul_f32_e32 v54, v59, v54
	v_mul_f32_e32 v53, v53, v54
	v_cvt_pk_bf16_f32 v52, v52, v53
	v_mul_f32_e32 v53, 0xbfb8aa3b, v60
	v_exp_f32_e32 v53, v53
	v_mul_f32_e32 v54, 0xbfb8aa3b, v61
	v_exp_f32_e32 v54, v54
	v_add_f32_e32 v53, 1.0, v53
	v_rcp_f32_e32 v53, v53
	v_add_f32_e32 v54, 1.0, v54
	v_rcp_f32_e32 v54, v54
	v_mul_f32_e32 v53, v60, v53
	v_mul_f32_e32 v53, v70, v53
	v_mul_f32_e32 v54, v61, v54
	v_mul_f32_e32 v54, v71, v54
	v_cvt_pk_bf16_f32 v53, v53, v54
	global_store_dwordx4 v[66:67], v[50:53], off
	v_pk_mul_f32 v[46:47], v[46:47], v[182:183] op_sel_hi:[1,0]
	v_pk_mul_f32 v[54:55], v[36:37], v[182:183] op_sel_hi:[1,0]
	v_pk_mul_f32 v[36:37], v[34:35], v[182:183] op_sel_hi:[1,0]
	v_mul_f32_e32 v34, 0xbfb8aa3b, v46
	v_mul_f32_e32 v35, 0xbfb8aa3b, v47
	v_exp_f32_e32 v34, v34
	v_exp_f32_e32 v35, v35
	v_pk_mul_f32 v[38:39], v[38:39], v[182:183] op_sel_hi:[1,0]
	v_pk_mul_f32 v[48:49], v[48:49], v[182:183] op_sel_hi:[1,0]
	v_add_f32_e32 v34, 1.0, v34
	v_add_f32_e32 v35, 1.0, v35
	v_rcp_f32_e32 v34, v34
	v_rcp_f32_e32 v35, v35
	v_pk_mul_f32 v[40:41], v[40:41], v[182:183] op_sel_hi:[1,0]
	v_pk_mul_f32 v[42:43], v[42:43], v[182:183] op_sel_hi:[1,0]
	v_mul_f32_e32 v34, v46, v34
	v_mul_f32_e32 v35, v47, v35
	v_mul_f32_e32 v34, v38, v34
	v_mul_f32_e32 v35, v39, v35
	v_cvt_pk_bf16_f32 v34, v34, v35
	v_mul_f32_e32 v35, 0xbfb8aa3b, v48
	v_mul_f32_e32 v38, 0xbfb8aa3b, v49
	v_exp_f32_e32 v35, v35
	v_exp_f32_e32 v38, v38
	v_pk_mul_f32 v[44:45], v[44:45], v[182:183] op_sel_hi:[1,0]
	v_add_u32_e32 v50, 0x90, v151
	v_add_f32_e32 v35, 1.0, v35
	v_add_f32_e32 v38, 1.0, v38
	v_rcp_f32_e32 v35, v35
	v_rcp_f32_e32 v38, v38
	v_mad_i64_i32 v[50:51], s[28:29], v50, s82, v[142:143]
	v_mul_f32_e32 v35, v48, v35
	v_mul_f32_e32 v38, v49, v38
	v_mul_f32_e32 v35, v40, v35
	v_mul_f32_e32 v38, v41, v38
	v_cvt_pk_bf16_f32 v35, v35, v38
	v_mul_f32_e32 v38, 0xbfb8aa3b, v42
	v_exp_f32_e32 v38, v38
	v_lshl_add_u64 v[50:51], v[50:51], 0, v[144:145]
	v_add_f32_e32 v38, 1.0, v38
	v_rcp_f32_e32 v38, v38
	s_nop 0
	v_mul_f32_e32 v38, v42, v38
	v_mul_f32_e32 v36, v36, v38
	v_mul_f32_e32 v38, 0xbfb8aa3b, v43
	v_exp_f32_e32 v38, v38
	s_nop 0
	v_add_f32_e32 v38, 1.0, v38
	v_rcp_f32_e32 v38, v38
	s_nop 0
	v_mul_f32_e32 v38, v43, v38
	v_mul_f32_e32 v37, v37, v38
	v_cvt_pk_bf16_f32 v36, v36, v37
	v_mul_f32_e32 v37, 0xbfb8aa3b, v44
	v_exp_f32_e32 v37, v37
	v_mul_f32_e32 v38, 0xbfb8aa3b, v45
	v_exp_f32_e32 v38, v38
	v_add_f32_e32 v37, 1.0, v37
	v_rcp_f32_e32 v37, v37
	v_add_f32_e32 v38, 1.0, v38
	v_rcp_f32_e32 v38, v38
	v_mul_f32_e32 v37, v44, v37
	v_mul_f32_e32 v37, v54, v37
	v_mul_f32_e32 v38, v45, v38
	v_mul_f32_e32 v38, v55, v38
	v_cvt_pk_bf16_f32 v37, v37, v38
	global_store_dwordx4 v[50:51], v[34:37], off
	v_pk_mul_f32 v[30:31], v[30:31], v[184:185] op_sel_hi:[1,0]
	v_pk_mul_f32 v[38:39], v[20:21], v[184:185] op_sel_hi:[1,0]
	v_pk_mul_f32 v[20:21], v[18:19], v[184:185] op_sel_hi:[1,0]
	v_mul_f32_e32 v18, 0xbfb8aa3b, v30
	v_mul_f32_e32 v19, 0xbfb8aa3b, v31
	v_exp_f32_e32 v18, v18
	v_exp_f32_e32 v19, v19
	v_pk_mul_f32 v[22:23], v[22:23], v[184:185] op_sel_hi:[1,0]
	v_pk_mul_f32 v[32:33], v[32:33], v[184:185] op_sel_hi:[1,0]
	v_add_f32_e32 v18, 1.0, v18
	v_add_f32_e32 v19, 1.0, v19
	v_rcp_f32_e32 v18, v18
	v_rcp_f32_e32 v19, v19
	v_pk_mul_f32 v[24:25], v[24:25], v[184:185] op_sel_hi:[1,0]
	v_pk_mul_f32 v[26:27], v[26:27], v[184:185] op_sel_hi:[1,0]
	v_mul_f32_e32 v18, v30, v18
	v_mul_f32_e32 v19, v31, v19
	v_mul_f32_e32 v18, v22, v18
	v_mul_f32_e32 v19, v23, v19
	v_cvt_pk_bf16_f32 v18, v18, v19
; __device__ __forceinline__ unsigned cvt_pk_bf16(float lo, float hi) { unsigned r; asm volatile("v_cvt_pk_bf16_f32 %0, %1, %2" : "=v"(r) : "v"(lo), "v"(hi)); return r; }
; __device__ __forceinline__ float silu_mul(float g, float u) { return g * __builtin_amdgcn_rcpf(1.0f + __expf(-g)) * u; }
;     __device__ __forceinline__ void operator()(const f32x4 (&acc)[2][2][4][2], const Unit& u, int wr, int wc, int fr, int fq) const {
;     ...
;             for (int m = 0; m < 4; ++m) { const int row = row0 + ai * HALF + m * 16; bf16_t* rowp = O + (size_t)row * ldc + col0; const float rsc = tab[wr * 64 + fr + ai * HALF + m * 16];
;                 const f32x4 g0 = acc[ai][0][m][0] * rsc, g1 = acc[ai][0][m][1] * rsc, u0 = acc[ai][1][m][0] * rsc, u1 = acc[ai][1][m][1] * rsc;
;                 u32x4 w;
;                 w.x = cvt_pk_bf16(silu_mul(g0[0], u0[0]), silu_mul(g0[1], u0[1])); w.y = cvt_pk_bf16(silu_mul(g0[2], u0[2]), silu_mul(g0[3], u0[3]));
;                 w.z = cvt_pk_bf16(silu_mul(g1[0], u1[0]), silu_mul(g1[1], u1[1])); w.w = cvt_pk_bf16(silu_mul(g1[2], u1[2]), silu_mul(g1[3], u1[3]));
;                 *(u32x4*)(rowp) = w; }
	v_mul_f32_e32 v19, 0xbfb8aa3b, v32
	v_mul_f32_e32 v22, 0xbfb8aa3b, v33
	v_exp_f32_e32 v19, v19
	v_exp_f32_e32 v22, v22
	v_pk_mul_f32 v[28:29], v[28:29], v[184:185] op_sel_hi:[1,0]
	v_add_u32_e32 v34, 0xa0, v151
	v_add_f32_e32 v19, 1.0, v19
	v_add_f32_e32 v22, 1.0, v22
	v_rcp_f32_e32 v19, v19
	v_rcp_f32_e32 v22, v22
	v_mad_i64_i32 v[34:35], s[28:29], v34, s82, v[142:143]
	v_mul_f32_e32 v19, v32, v19
	v_mul_f32_e32 v22, v33, v22
	v_mul_f32_e32 v19, v24, v19
	v_mul_f32_e32 v22, v25, v22
	v_cvt_pk_bf16_f32 v19, v19, v22
	v_mul_f32_e32 v22, 0xbfb8aa3b, v26
	v_exp_f32_e32 v22, v22
	v_lshl_add_u64 v[34:35], v[34:35], 0, v[144:145]
	v_add_f32_e32 v22, 1.0, v22
	v_rcp_f32_e32 v22, v22
	s_nop 0
	v_mul_f32_e32 v22, v26, v22
	v_mul_f32_e32 v20, v20, v22
	v_mul_f32_e32 v22, 0xbfb8aa3b, v27
	v_exp_f32_e32 v22, v22
	s_nop 0
	v_add_f32_e32 v22, 1.0, v22
	v_rcp_f32_e32 v22, v22
	s_nop 0
	v_mul_f32_e32 v22, v27, v22
	v_mul_f32_e32 v21, v21, v22
	v_cvt_pk_bf16_f32 v20, v20, v21
	v_mul_f32_e32 v21, 0xbfb8aa3b, v28
	v_exp_f32_e32 v21, v21
	v_mul_f32_e32 v22, 0xbfb8aa3b, v29
	v_exp_f32_e32 v22, v22
	v_add_f32_e32 v21, 1.0, v21
	v_rcp_f32_e32 v21, v21
	v_add_f32_e32 v22, 1.0, v22
	v_rcp_f32_e32 v22, v22
	v_mul_f32_e32 v21, v28, v21
	v_mul_f32_e32 v21, v38, v21
	v_mul_f32_e32 v22, v29, v22
	v_mul_f32_e32 v22, v39, v22
	v_cvt_pk_bf16_f32 v21, v21, v22
	global_store_dwordx4 v[34:35], v[18:21], off
	v_pk_mul_f32 v[14:15], v[14:15], v[186:187] op_sel_hi:[1,0]
	v_pk_mul_f32 v[16:17], v[16:17], v[186:187] op_sel_hi:[1,0]
	v_pk_mul_f32 v[12:13], v[12:13], v[186:187] op_sel_hi:[1,0]
	v_pk_mul_f32 v[10:11], v[10:11], v[186:187] op_sel_hi:[1,0]
	v_pk_mul_f32 v[8:9], v[8:9], v[186:187] op_sel_hi:[1,0]
	v_pk_mul_f32 v[6:7], v[6:7], v[186:187] op_sel_hi:[1,0]
	v_pk_mul_f32 v[20:21], v[4:5], v[186:187] op_sel_hi:[1,0]
	v_pk_mul_f32 v[4:5], v[2:3], v[186:187] op_sel_hi:[1,0]
	v_mul_f32_e32 v0, 0xbfb8aa3b, v14
	v_mul_f32_e32 v2, 0xbfb8aa3b, v15
	v_exp_f32_e32 v0, v0
	v_exp_f32_e32 v2, v2
	v_mul_f32_e32 v3, 0xbfb8aa3b, v17
	v_exp_f32_e32 v3, v3
	v_add_f32_e32 v0, 1.0, v0
	v_add_f32_e32 v2, 1.0, v2
	v_rcp_f32_e32 v0, v0
	v_rcp_f32_e32 v2, v2
	v_add_f32_e32 v3, 1.0, v3
	v_rcp_f32_e32 v3, v3
	v_mul_f32_e32 v0, v14, v0
	v_mul_f32_e32 v2, v15, v2
	v_mul_f32_e32 v0, v6, v0
	v_mul_f32_e32 v2, v7, v2
	v_cvt_pk_bf16_f32 v2, v0, v2
	v_mul_f32_e32 v0, 0xbfb8aa3b, v16
	v_exp_f32_e32 v0, v0
	v_mul_f32_e32 v3, v17, v3
	v_mul_f32_e32 v3, v9, v3
	v_add_u32_e32 v18, 0xb0, v151
	v_add_f32_e32 v0, 1.0, v0
	v_rcp_f32_e32 v0, v0
	v_mad_i64_i32 v[18:19], s[28:29], v18, s82, v[142:143]
	v_lshl_add_u64 v[18:19], v[18:19], 0, v[144:145]
	v_mul_f32_e32 v0, v16, v0
	v_mul_f32_e32 v0, v8, v0
	v_cvt_pk_bf16_f32 v3, v0, v3
	v_mul_f32_e32 v0, 0xbfb8aa3b, v10
	v_exp_f32_e32 v0, v0
	s_mov_b64 s[28:29], -1
	v_add_f32_e32 v0, 1.0, v0
	v_rcp_f32_e32 v0, v0
	s_nop 0
	v_mul_f32_e32 v0, v10, v0
	v_mul_f32_e32 v0, v4, v0
	v_mul_f32_e32 v4, 0xbfb8aa3b, v11
	v_exp_f32_e32 v4, v4
	s_nop 0
	v_add_f32_e32 v4, 1.0, v4
	v_rcp_f32_e32 v4, v4
	s_nop 0
	v_mul_f32_e32 v4, v11, v4
	v_mul_f32_e32 v4, v5, v4
	v_mul_f32_e32 v5, 0xbfb8aa3b, v13
	v_cvt_pk_bf16_f32 v4, v0, v4
	v_mul_f32_e32 v0, 0xbfb8aa3b, v12
	v_exp_f32_e32 v5, v5
	v_exp_f32_e32 v0, v0
	v_add_f32_e32 v5, 1.0, v5
	v_add_f32_e32 v0, 1.0, v0
	v_rcp_f32_e32 v5, v5
	v_rcp_f32_e32 v0, v0
	v_mul_f32_e32 v5, v13, v5
	v_mul_f32_e32 v0, v12, v0
	v_mul_f32_e32 v5, v21, v5
	v_mul_f32_e32 v0, v20, v0
	v_cvt_pk_bf16_f32 v5, v0, v5
	global_store_dwordx4 v[18:19], v[2:5], off
	s_cbranch_vccnz .LBB0_630
	s_andn2_b64 vcc, exec, s[8:9]
	s_cbranch_vccnz .LBB0_629
	s_barrier
	s_branch .LBB0_629
